# SGU part: the attention part's Q/gain loads are issued behind the u rows and waited with counted vmcnt, so the u rows arrive first
# baseline (speedup 1.0000x reference)
; __device__ __forceinline__ float bflo(unsigned w) { return __uint_as_float(w << 16); }
; __device__ __forceinline__ float bfhi(unsigned w) { return __uint_as_float(w & 0xffff0000u); }
; __device__ __forceinline__ void mixer_phase256(const Args& A, int l, int vc, const bf16* Z, bf16* MIX, ss_t* ssa, ss_t* ssb, unsigned char* lds, int tid, int wid, int lane) {
;     ...
;     { const float* gs = A.sgu_norm_g + (l * 16 + h) * 64; float ss = 0.f; bf16* vn = VN + sj * 64 * VN_STRIDE;
; #pragma unroll
;       for (int c = 0; c < 8; ++c)
; #pragma unroll
;           for (int e = 0; e < 4; ++e) { const float a = bflo(sw[c][e]), b = bfhi(sw[c][e]); ss += a * a + b * b; }
;       const float rstd = 1.0f / sqrtf(ss * (1.0f / 64.f) + EPS);
; #pragma unroll
;       for (int c = 0; c < 8; ++c) { const f32x4 g0 = *(const f32x4*)(gs + 8 * c), g1 = *(const f32x4*)(gs + 8 * c + 4); const float gg[8] = {g0.x, g0.y, g0.z, g0.w, g1.x, g1.y, g1.z, g1.w};
.LBB0_520:
	s_or_b64 exec, exec, s[12:13]
	v_and_b32_e32 v91, 0xffff0000, v65
	v_and_b32_e32 v90, 0xffff0000, v64
	s_lshl_b32 s76, s38, 6
	s_movk_i32 s2, 0x4400
	v_lshlrev_b32_e32 v89, 16, v65
	v_lshlrev_b32_e32 v88, 16, v64
	v_pk_mul_f32 v[0:1], v[90:91], v[90:91]
	v_and_b32_e32 v87, 0xffff0000, v67
	v_and_b32_e32 v86, 0xffff0000, v66
	v_mul_lo_u32 v77, v177, s2
	v_pk_fma_f32 v[104:105], v[88:89], v[88:89], v[0:1]
	v_lshlrev_b32_e32 v85, 16, v67
	v_lshlrev_b32_e32 v84, 16, v66
	v_pk_mul_f32 v[0:1], v[86:87], v[86:87]
	v_and_b32_e32 v83, 0xffff0000, v61
	v_and_b32_e32 v82, 0xffff0000, v60
	s_lshl_b64 s[2:3], s[76:77], 2
	v_pk_fma_f32 v[106:107], v[84:85], v[84:85], v[0:1]
	v_lshlrev_b32_e32 v81, 16, v61
	v_lshlrev_b32_e32 v80, 16, v60
	v_pk_mul_f32 v[0:1], v[82:83], v[82:83]
	v_and_b32_e32 v79, 0xffff0000, v63
	v_and_b32_e32 v78, 0xffff0000, v62
	s_add_u32 s12, s48, s2
	v_pk_fma_f32 v[108:109], v[80:81], v[80:81], v[0:1]
	v_lshlrev_b32_e32 v1, 16, v63
	v_lshlrev_b32_e32 v0, 16, v62
	v_pk_mul_f32 v[60:61], v[78:79], v[78:79]
	s_addc_u32 s13, s49, s3
	v_pk_fma_f32 v[110:111], v[0:1], v[0:1], v[60:61]
	global_load_dwordx4 v[60:63], v2, s[12:13] offset:48
	global_load_dwordx4 v[64:67], v2, s[12:13] offset:32
	global_load_dwordx4 v[68:71], v2, s[12:13] offset:16
	global_load_dwordx4 v[72:75], v2, s[12:13]
	v_lshlrev_b32_e32 v136, 16, v56
	v_and_b32_e32 v137, 0xffff0000, v56
	v_lshlrev_b32_e32 v138, 16, v57
	v_and_b32_e32 v139, 0xffff0000, v57
	v_pk_mul_f32 v[116:117], v[136:137], v[136:137]
	v_pk_mul_f32 v[118:119], v[138:139], v[138:139]
	v_lshlrev_b32_e32 v140, 16, v58
	v_and_b32_e32 v141, 0xffff0000, v58
	v_pk_mul_f32 v[120:121], v[140:141], v[140:141]
	v_lshlrev_b32_e32 v142, 16, v59
	v_and_b32_e32 v143, 0xffff0000, v59
	v_add_f32_e32 v118, v118, v119
	v_add_f32_e32 v116, v116, v117
	v_pk_mul_f32 v[122:123], v[142:143], v[142:143]
	v_lshlrev_b32_e32 v144, 16, v52
	v_and_b32_e32 v145, 0xffff0000, v52
	v_add_f32_e32 v116, v116, v118
	v_add_f32_e32 v117, v120, v121
	v_pk_mul_f32 v[124:125], v[144:145], v[144:145]
	v_lshlrev_b32_e32 v146, 16, v53
	v_and_b32_e32 v147, 0xffff0000, v53
	v_add_f32_e32 v115, v122, v123
	v_add_f32_e32 v116, v117, v116
	v_pk_mul_f32 v[126:127], v[146:147], v[146:147]
	v_lshlrev_b32_e32 v148, 16, v54
	v_and_b32_e32 v149, 0xffff0000, v54
	v_add_f32_e32 v115, v115, v116
	v_add_f32_e32 v116, v124, v125
	v_pk_mul_f32 v[128:129], v[148:149], v[148:149]
	v_lshlrev_b32_e32 v150, 16, v55
	v_and_b32_e32 v151, 0xffff0000, v55
	v_add_f32_e32 v115, v116, v115
	v_add_f32_e32 v116, v126, v127
	v_pk_mul_f32 v[130:131], v[150:151], v[150:151]
	v_lshlrev_b32_e32 v152, 16, v48
	v_and_b32_e32 v153, 0xffff0000, v48
	v_add_f32_e32 v115, v116, v115
	v_add_f32_e32 v116, v128, v129
	v_pk_mul_f32 v[132:133], v[152:153], v[152:153]
	v_lshlrev_b32_e32 v154, 16, v49
	v_and_b32_e32 v155, 0xffff0000, v49
	v_add_f32_e32 v115, v116, v115
	v_add_f32_e32 v116, v130, v131
	v_pk_mul_f32 v[134:135], v[154:155], v[154:155]
	v_lshlrev_b32_e32 v92, 16, v50
	v_and_b32_e32 v93, 0xffff0000, v50
	v_add_f32_e32 v115, v116, v115
	v_add_f32_e32 v116, v132, v133
	v_pk_mul_f32 v[156:157], v[92:93], v[92:93]
	v_lshlrev_b32_e32 v48, 16, v51
	v_and_b32_e32 v49, 0xffff0000, v51
	v_add_f32_e32 v115, v116, v115
	v_add_f32_e32 v116, v134, v135
	v_pk_mul_f32 v[158:159], v[48:49], v[48:49]
	v_lshlrev_b32_e32 v96, 16, v44
	v_and_b32_e32 v97, 0xffff0000, v44
	v_add_f32_e32 v115, v116, v115
	v_add_f32_e32 v116, v156, v157
	v_pk_mul_f32 v[172:173], v[96:97], v[96:97]
	v_lshlrev_b32_e32 v94, 16, v45
	v_and_b32_e32 v95, 0xffff0000, v45
	v_add_f32_e32 v115, v116, v115
	v_add_f32_e32 v116, v158, v159
	v_pk_mul_f32 v[178:179], v[94:95], v[94:95]
	v_lshlrev_b32_e32 v50, 16, v46
	v_and_b32_e32 v51, 0xffff0000, v46
	v_add_f32_e32 v115, v116, v115
	v_add_f32_e32 v116, v172, v173
	v_pk_mul_f32 v[180:181], v[50:51], v[50:51]
	v_lshlrev_b32_e32 v44, 16, v47
	v_and_b32_e32 v45, 0xffff0000, v47
	v_add_f32_e32 v115, v116, v115
	v_add_f32_e32 v116, v178, v179
	v_pk_mul_f32 v[182:183], v[44:45], v[44:45]
	v_lshlrev_b32_e32 v46, 16, v8
	v_and_b32_e32 v47, 0xffff0000, v8
	v_add_f32_e32 v115, v116, v115
	v_add_f32_e32 v116, v180, v181
	v_pk_mul_f32 v[184:185], v[46:47], v[46:47]
	v_lshlrev_b32_e32 v8, 16, v9
	v_and_b32_e32 v9, 0xffff0000, v9
	v_add_f32_e32 v115, v116, v115
	v_add_f32_e32 v116, v182, v183
	v_pk_mul_f32 v[186:187], v[8:9], v[8:9]
	v_lshlrev_b32_e32 v98, 16, v10
	v_and_b32_e32 v99, 0xffff0000, v10
	v_add_f32_e32 v115, v116, v115
	v_add_f32_e32 v116, v184, v185
	v_pk_mul_f32 v[188:189], v[98:99], v[98:99]
	v_lshlrev_b32_e32 v10, 16, v11
	v_and_b32_e32 v11, 0xffff0000, v11
	v_add_f32_e32 v115, v116, v115
	v_add_f32_e32 v116, v186, v187
	v_pk_mul_f32 v[190:191], v[10:11], v[10:11]
	v_lshlrev_b32_e32 v100, 16, v4
	v_and_b32_e32 v101, 0xffff0000, v4
	v_add_f32_e32 v115, v116, v115
	v_add_f32_e32 v116, v188, v189
	global_load_dwordx4 v[52:55], v2, s[12:13] offset:80
	global_load_dwordx4 v[56:59], v2, s[12:13] offset:64
	v_pk_mul_f32 v[192:193], v[100:101], v[100:101]
	v_lshlrev_b32_e32 v4, 16, v5
	v_and_b32_e32 v5, 0xffff0000, v5
	v_add_f32_e32 v115, v116, v115
	v_add_f32_e32 v116, v190, v191
	v_pk_mul_f32 v[194:195], v[4:5], v[4:5]
	v_lshlrev_b32_e32 v102, 16, v6
	v_and_b32_e32 v103, 0xffff0000, v6
	v_add_f32_e32 v115, v116, v115
	v_add_f32_e32 v116, v192, v193
	v_pk_mul_f32 v[196:197], v[102:103], v[102:103]
	v_lshlrev_b32_e32 v6, 16, v7
	v_and_b32_e32 v7, 0xffff0000, v7
	v_add_f32_e32 v115, v116, v115
	v_add_f32_e32 v116, v194, v195
	v_pk_mul_f32 v[198:199], v[6:7], v[6:7]
	v_add_f32_e32 v115, v116, v115
	v_add_f32_e32 v116, v196, v197
	v_add_f32_e32 v115, v116, v115
; __device__ __forceinline__ unsigned pkbf(float lo, float hi) { typedef float f2_t __attribute__((ext_vector_type(2))); typedef __bf16 b2_t __attribute__((ext_vector_type(2))); f2_t v = {lo, hi}; b2_t b = __builtin_convertvector(v, b2_t); return __builtin_bit_cast(unsigned, b); }
; __device__ __forceinline__ float bflo(unsigned w) { return __uint_as_float(w << 16); }
; __device__ __forceinline__ float bfhi(unsigned w) { return __uint_as_float(w & 0xffff0000u); }
; __device__ __forceinline__ void mixer_phase256(const Args& A, int l, int vc, const bf16* Z, bf16* MIX, ss_t* ssa, ss_t* ssb, unsigned char* lds, int tid, int wid, int lane) {
;     ...
;       const float rstd = 1.0f / sqrtf(ss * (1.0f / 64.f) + EPS);
; #pragma unroll
;       for (int c = 0; c < 8; ++c) { const f32x4 g0 = *(const f32x4*)(gs + 8 * c), g1 = *(const f32x4*)(gs + 8 * c + 4); const float gg[8] = {g0.x, g0.y, g0.z, g0.w, g1.x, g1.y, g1.z, g1.w};
; #pragma unroll
;           for (int e = 0; e < 4; ++e) { const unsigned w = pkbf(bflo(sw[c][e]) * rstd * gg[2 * e], bfhi(sw[c][e]) * rstd * gg[2 * e + 1]);
;               vn[(8 * c + 2 * e) * VN_STRIDE + srow] = (bf16)(w & 0xffffu); vn[(8 * c + 2 * e + 1) * VN_STRIDE + srow] = (bf16)(w >> 16); } }
	v_add_f32_e32 v116, v198, v199
	v_add_f32_e32 v115, v116, v115
	v_add_f32_e32 v104, v104, v115
	v_add_f32_e32 v104, v105, v104
	v_add_f32_e32 v104, v106, v104
	v_add_f32_e32 v104, v107, v104
	v_add_f32_e32 v104, v108, v104
	v_add_f32_e32 v104, v109, v104
	global_load_dwordx4 v[106:109], v2, s[12:13] offset:112
	global_load_dwordx4 v[116:119], v2, s[12:13] offset:96
	v_add_f32_e32 v104, v110, v104
	v_add_f32_e32 v104, v111, v104
	v_fmamk_f32 v104, v104, 0x3c800000, v205
	v_mul_f32_e32 v105, 0x4f800000, v104
	v_cmp_gt_f32_e32 vcc, s97, v104
	v_lshlrev_b32_e32 v3, 1, v3
	v_readlane_b32 s14, v247, 27
	v_cndmask_b32_e32 v104, v104, v105, vcc
	v_sqrt_f32_e32 v105, v104
	v_add3_u32 v3, s14, v77, v3
	global_load_dwordx4 v[120:123], v2, s[12:13] offset:176
	global_load_dwordx4 v[124:127], v2, s[12:13] offset:160
	global_load_dwordx4 v[128:131], v2, s[12:13] offset:144
	global_load_dwordx4 v[132:135], v2, s[12:13] offset:128
	v_lshlrev_b32_e32 v76, 3, v176
	v_add_u32_e32 v77, -1, v105
	v_fma_f32 v110, -v77, v105, v104
	v_cmp_ge_f32_e64 s[2:3], 0, v110
	v_add_u32_e32 v110, 1, v105
	s_nop 0
	v_cndmask_b32_e64 v77, v105, v77, s[2:3]
	v_fma_f32 v105, -v110, v105, v104
	v_cmp_lt_f32_e64 s[2:3], 0, v105
	s_nop 1
	v_cndmask_b32_e64 v77, v77, v110, s[2:3]
	v_mul_f32_e32 v105, 0x37800000, v77
	v_cndmask_b32_e32 v77, v77, v105, vcc
	v_cmp_class_f32_e32 vcc, v104, v206
	s_nop 1
	v_cndmask_b32_e32 v77, v77, v104, vcc
	v_div_scale_f32 v104, s[2:3], v77, v77, 1.0
	v_rcp_f32_e32 v105, v104
	s_and_b32 s2, s17, 64
	v_readlane_b32 s3, v248, 1
	s_or_b32 s2, s3, s2
	v_fma_f32 v110, -v104, v105, 1.0
	v_fmac_f32_e32 v105, v110, v105
	v_div_scale_f32 v110, vcc, 1.0, v77, 1.0
	v_mul_f32_e32 v111, v110, v105
	v_fma_f32 v115, -v104, v111, v110
	v_fmac_f32_e32 v111, v115, v105
	v_fma_f32 v104, -v104, v111, v110
	v_div_fmas_f32 v104, v104, v105, v111
	v_div_fixup_f32 v104, v104, v77, 1.0
	v_pk_mul_f32 v[110:111], v[104:105], v[136:137] op_sel_hi:[0,1]
	s_waitcnt vmcnt(8)
	v_pk_mul_f32 v[72:73], v[110:111], v[72:73]
	v_pk_mul_f32 v[48:49], v[104:105], v[48:49] op_sel_hi:[0,1]
	v_cvt_pk_bf16_f32 v72, v72, v73
	ds_write_b16 v3, v72
	ds_write_b16_d16_hi v3, v72 offset:272
	v_pk_mul_f32 v[72:73], v[104:105], v[138:139] op_sel_hi:[0,1]
	v_pk_mul_f32 v[72:73], v[72:73], v[74:75]
	s_waitcnt vmcnt(7)
	v_pk_mul_f32 v[48:49], v[48:49], v[54:55]
	v_cvt_pk_bf16_f32 v72, v72, v73
	ds_write_b16 v3, v72 offset:544
	ds_write_b16_d16_hi v3, v72 offset:816
	v_pk_mul_f32 v[72:73], v[104:105], v[140:141] op_sel_hi:[0,1]
	v_pk_mul_f32 v[68:69], v[72:73], v[68:69]
	v_cvt_pk_bf16_f32 v48, v48, v49
	v_cvt_pk_bf16_f32 v68, v68, v69
	ds_write_b16 v3, v68 offset:1088
	ds_write_b16_d16_hi v3, v68 offset:1360
	v_pk_mul_f32 v[68:69], v[104:105], v[142:143] op_sel_hi:[0,1]
	v_pk_mul_f32 v[68:69], v[68:69], v[70:71]
	v_pk_mul_f32 v[44:45], v[104:105], v[44:45] op_sel_hi:[0,1]
	v_cvt_pk_bf16_f32 v68, v68, v69
	ds_write_b16 v3, v68 offset:1632
	ds_write_b16_d16_hi v3, v68 offset:1904
	v_pk_mul_f32 v[68:69], v[104:105], v[144:145] op_sel_hi:[0,1]
	v_pk_mul_f32 v[64:65], v[68:69], v[64:65]
	v_pk_mul_f32 v[8:9], v[104:105], v[8:9] op_sel_hi:[0,1]
	v_cvt_pk_bf16_f32 v64, v64, v65
	ds_write_b16 v3, v64 offset:2176
	ds_write_b16_d16_hi v3, v64 offset:2448
	v_pk_mul_f32 v[64:65], v[104:105], v[146:147] op_sel_hi:[0,1]
	v_pk_mul_f32 v[64:65], v[64:65], v[66:67]
	v_pk_mul_f32 v[4:5], v[104:105], v[4:5] op_sel_hi:[0,1]
	v_cvt_pk_bf16_f32 v64, v64, v65
	ds_write_b16 v3, v64 offset:2720
	ds_write_b16_d16_hi v3, v64 offset:2992
	v_pk_mul_f32 v[64:65], v[104:105], v[148:149] op_sel_hi:[0,1]
	v_pk_mul_f32 v[60:61], v[64:65], v[60:61]
	v_mov_b32_e32 v77, v2
	v_cvt_pk_bf16_f32 v60, v60, v61
	ds_write_b16 v3, v60 offset:3264
	ds_write_b16_d16_hi v3, v60 offset:3536
	v_pk_mul_f32 v[60:61], v[104:105], v[150:151] op_sel_hi:[0,1]
	v_pk_mul_f32 v[60:61], v[60:61], v[62:63]
	s_waitcnt vmcnt(5)
	v_pk_mul_f32 v[44:45], v[44:45], v[108:109]
	v_cvt_pk_bf16_f32 v60, v60, v61
	ds_write_b16 v3, v60 offset:3808
	ds_write_b16_d16_hi v3, v60 offset:4080
	v_pk_mul_f32 v[60:61], v[104:105], v[152:153] op_sel_hi:[0,1]
	v_pk_mul_f32 v[56:57], v[60:61], v[56:57]
	v_cvt_pk_bf16_f32 v44, v44, v45
	v_cvt_pk_bf16_f32 v56, v56, v57
	ds_write_b16 v3, v56 offset:4352
	ds_write_b16_d16_hi v3, v56 offset:4624
	global_load_dwordx4 v[60:63], v2, s[12:13] offset:208
	global_load_dwordx4 v[64:67], v2, s[12:13] offset:192
	v_pk_mul_f32 v[56:57], v[104:105], v[154:155] op_sel_hi:[0,1]
	v_pk_mul_f32 v[56:57], v[56:57], v[58:59]
	s_waitcnt vmcnt(2)
; __device__ __forceinline__ unsigned pkbf(float lo, float hi) { typedef float f2_t __attribute__((ext_vector_type(2))); typedef __bf16 b2_t __attribute__((ext_vector_type(2))); f2_t v = {lo, hi}; b2_t b = __builtin_convertvector(v, b2_t); return __builtin_bit_cast(unsigned, b); }
; __device__ __forceinline__ float bflo(unsigned w) { return __uint_as_float(w << 16); }
; __device__ __forceinline__ float bfhi(unsigned w) { return __uint_as_float(w & 0xffff0000u); }
; __device__ __forceinline__ void mixer_phase256(const Args& A, int l, int vc, const bf16* Z, bf16* MIX, ss_t* ssa, ss_t* ssb, unsigned char* lds, int tid, int wid, int lane) {
;     ...
;       for (int c = 0; c < 8; ++c) { const f32x4 g0 = *(const f32x4*)(gs + 8 * c), g1 = *(const f32x4*)(gs + 8 * c + 4); const float gg[8] = {g0.x, g0.y, g0.z, g0.w, g1.x, g1.y, g1.z, g1.w};
; #pragma unroll
;           for (int e = 0; e < 4; ++e) { const unsigned w = pkbf(bflo(sw[c][e]) * rstd * gg[2 * e], bfhi(sw[c][e]) * rstd * gg[2 * e + 1]);
;               vn[(8 * c + 2 * e) * VN_STRIDE + srow] = (bf16)(w & 0xffffu); vn[(8 * c + 2 * e + 1) * VN_STRIDE + srow] = (bf16)(w >> 16); } }
;     }
;     asm volatile("" ::: "memory");
;     u32x4 q0[2]; attn_load_q(q0, Z, n, kvh, wid, lane);
;     u32x2 uw[4][4];
; #pragma unroll
;     for (int j = 0; j < 4; ++j)
; #pragma unroll
;         for (int dt = 0; dt < 4; ++dt) uw[j][dt] = *(const u32x2*)(Z + (size_t)((cb + j) * 128 + st) * INW + h * 64 + 16 * dt + 4 * fq);
	v_pk_mul_f32 v[8:9], v[8:9], v[134:135]
	v_cvt_pk_bf16_f32 v56, v56, v57
	ds_write_b16 v3, v56 offset:4896
	ds_write_b16_d16_hi v3, v56 offset:5168
	v_pk_mul_f32 v[56:57], v[104:105], v[92:93] op_sel_hi:[0,1]
	v_pk_mul_f32 v[52:53], v[56:57], v[52:53]
	v_cvt_pk_bf16_f32 v8, v8, v9
	v_cvt_pk_bf16_f32 v52, v52, v53
	ds_write_b16 v3, v52 offset:5440
	ds_write_b16_d16_hi v3, v52 offset:5712
	ds_write_b16 v3, v48 offset:5984
	ds_write_b16_d16_hi v3, v48 offset:6256
	v_pk_mul_f32 v[48:49], v[104:105], v[96:97] op_sel_hi:[0,1]
	v_pk_mul_f32 v[48:49], v[48:49], v[116:117]
	v_pk_mul_f32 v[4:5], v[4:5], v[126:127]
	v_cvt_pk_bf16_f32 v48, v48, v49
	ds_write_b16 v3, v48 offset:6528
	ds_write_b16_d16_hi v3, v48 offset:6800
	v_pk_mul_f32 v[48:49], v[104:105], v[94:95] op_sel_hi:[0,1]
	v_pk_mul_f32 v[48:49], v[48:49], v[118:119]
	v_cvt_pk_bf16_f32 v4, v4, v5
	v_cvt_pk_bf16_f32 v48, v48, v49
	ds_write_b16 v3, v48 offset:7072
	ds_write_b16_d16_hi v3, v48 offset:7344
	global_load_dwordx4 v[52:55], v2, s[12:13] offset:240
	global_load_dwordx4 v[56:59], v2, s[12:13] offset:224
	v_pk_mul_f32 v[48:49], v[104:105], v[50:51] op_sel_hi:[0,1]
	v_pk_mul_f32 v[48:49], v[48:49], v[106:107]
	s_nop 0
	v_cvt_pk_bf16_f32 v48, v48, v49
	ds_write_b16 v3, v48 offset:7616
	ds_write_b16_d16_hi v3, v48 offset:7888
	ds_write_b16 v3, v44 offset:8160
	ds_write_b16_d16_hi v3, v44 offset:8432
	v_pk_mul_f32 v[44:45], v[104:105], v[46:47] op_sel_hi:[0,1]
	v_pk_mul_f32 v[44:45], v[44:45], v[132:133]
	s_nop 0
	v_cvt_pk_bf16_f32 v44, v44, v45
	ds_write_b16 v3, v44 offset:8704
	ds_write_b16_d16_hi v3, v44 offset:8976
	ds_write_b16 v3, v8 offset:9248
	ds_write_b16_d16_hi v3, v8 offset:9520
	v_pk_mul_f32 v[8:9], v[104:105], v[98:99] op_sel_hi:[0,1]
	v_pk_mul_f32 v[8:9], v[8:9], v[128:129]
	v_mov_b32_e32 v45, v2
	v_cvt_pk_bf16_f32 v8, v8, v9
	ds_write_b16 v3, v8 offset:9792
	ds_write_b16_d16_hi v3, v8 offset:10064
	v_pk_mul_f32 v[8:9], v[104:105], v[10:11] op_sel_hi:[0,1]
	v_pk_mul_f32 v[8:9], v[8:9], v[130:131]
	s_nop 0
	v_cvt_pk_bf16_f32 v8, v8, v9
	ds_write_b16 v3, v8 offset:10336
	ds_write_b16_d16_hi v3, v8 offset:10608
	v_pk_mul_f32 v[8:9], v[104:105], v[100:101] op_sel_hi:[0,1]
	v_pk_mul_f32 v[8:9], v[8:9], v[124:125]
	s_nop 0
	v_cvt_pk_bf16_f32 v8, v8, v9
	ds_write_b16 v3, v8 offset:10880
	ds_write_b16_d16_hi v3, v8 offset:11152
	ds_write_b16 v3, v4 offset:11424
	ds_write_b16_d16_hi v3, v4 offset:11696
	v_pk_mul_f32 v[4:5], v[104:105], v[102:103] op_sel_hi:[0,1]
	v_pk_mul_f32 v[4:5], v[4:5], v[120:121]
	s_nop 0
	v_cvt_pk_bf16_f32 v4, v4, v5
	ds_write_b16 v3, v4 offset:11968
	ds_write_b16_d16_hi v3, v4 offset:12240
	v_pk_mul_f32 v[4:5], v[104:105], v[6:7] op_sel_hi:[0,1]
	v_pk_mul_f32 v[4:5], v[4:5], v[122:123]
	s_nop 0
	v_cvt_pk_bf16_f32 v4, v4, v5
	ds_write_b16 v3, v4 offset:12512
	ds_write_b16_d16_hi v3, v4 offset:12784
	v_mov_b32_e32 v4, v88
	v_mov_b32_e32 v5, v90
	v_pk_mul_f32 v[4:5], v[104:105], v[4:5] op_sel_hi:[0,1]
	v_mov_b32_e32 v90, v89
	s_waitcnt vmcnt(2)
	v_pk_mul_f32 v[4:5], v[4:5], v[64:65]
	s_nop 0
	v_cvt_pk_bf16_f32 v4, v4, v5
	ds_write_b16 v3, v4 offset:13056
	ds_write_b16_d16_hi v3, v4 offset:13328
	v_pk_mul_f32 v[4:5], v[104:105], v[90:91] op_sel_hi:[0,1]
	v_pk_mul_f32 v[4:5], v[4:5], v[66:67]
	s_nop 0
	v_cvt_pk_bf16_f32 v4, v4, v5
	ds_write_b16 v3, v4 offset:13600
	ds_write_b16_d16_hi v3, v4 offset:13872
	v_mov_b32_e32 v4, v84
	v_mov_b32_e32 v5, v86
	v_pk_mul_f32 v[4:5], v[104:105], v[4:5] op_sel_hi:[0,1]
	v_pk_mul_f32 v[4:5], v[4:5], v[60:61]
	v_mov_b32_e32 v86, v85
	v_cvt_pk_bf16_f32 v4, v4, v5
	ds_write_b16 v3, v4 offset:14144
	ds_write_b16_d16_hi v3, v4 offset:14416
	v_pk_mul_f32 v[4:5], v[104:105], v[86:87] op_sel_hi:[0,1]
	v_pk_mul_f32 v[4:5], v[4:5], v[62:63]
	s_nop 0
	v_cvt_pk_bf16_f32 v4, v4, v5
	ds_write_b16 v3, v4 offset:14688
	ds_write_b16_d16_hi v3, v4 offset:14960
	v_mov_b32_e32 v4, v80
	v_mov_b32_e32 v5, v82
	v_pk_mul_f32 v[4:5], v[104:105], v[4:5] op_sel_hi:[0,1]
	s_waitcnt vmcnt(0)
	v_pk_mul_f32 v[4:5], v[4:5], v[56:57]
	v_mov_b32_e32 v82, v81
	v_cvt_pk_bf16_f32 v4, v4, v5
	ds_write_b16 v3, v4 offset:15232
	ds_write_b16_d16_hi v3, v4 offset:15504
	v_pk_mul_f32 v[4:5], v[104:105], v[82:83] op_sel_hi:[0,1]
	v_pk_mul_f32 v[4:5], v[4:5], v[58:59]
	s_nop 0
	v_cvt_pk_bf16_f32 v4, v4, v5
	ds_write_b16 v3, v4 offset:15776
	ds_write_b16_d16_hi v3, v4 offset:16048
	v_mov_b32_e32 v4, v0
	v_mov_b32_e32 v5, v78
	v_pk_mul_f32 v[4:5], v[104:105], v[4:5] op_sel_hi:[0,1]
	v_pk_mul_f32 v[4:5], v[4:5], v[52:53]
	v_mov_b32_e32 v78, v1
	v_cvt_pk_bf16_f32 v0, v4, v5
	ds_write_b16 v3, v0 offset:16320
	ds_write_b16_d16_hi v3, v0 offset:16592
	v_pk_mul_f32 v[0:1], v[104:105], v[78:79] op_sel_hi:[0,1]
	v_pk_mul_f32 v[0:1], v[0:1], v[54:55]
	s_nop 0
	v_cvt_pk_bf16_f32 v0, v0, v1
	ds_write_b16 v3, v0 offset:16864
	ds_write_b16_d16_hi v3, v0 offset:17136
	v_or_b32_e32 v3, s2, v175
	v_mov_b64_e32 v[0:1], s[82:83]
	v_mad_i64_i32 v[0:1], s[2:3], v3, s85, v[0:1]
	s_lshl_b32 s2, s73, 5
	s_andn2_b32 s2, s2, 63
	v_readlane_b32 s3, v248, 0
	s_add_i32 s2, s2, s3
	v_lshrrev_b32_e32 v3, 1, v113
	s_ashr_i32 s3, s2, 31
	v_and_b32_e32 v3, 24, v3
	v_lshl_add_u64 v[0:1], s[2:3], 1, v[0:1]
	v_lshlrev_b32_e32 v44, 1, v3
	v_lshl_add_u64 v[0:1], v[0:1], 0, v[44:45]
	s_mov_b64 s[2:3], 0x1000
	v_lshl_add_u64 v[8:9], v[0:1], 0, s[2:3]
	s_movk_i32 s2, 0x1000
	v_add_co_u32_e32 v0, vcc, s2, v0
	v_readlane_b32 s2, v248, 4
	s_nop 0
	v_addc_co_u32_e32 v1, vcc, 0, v1, vcc
	v_readlane_b32 s3, v248, 5
	s_nop 0
	s_nop 0
	s_nop 0
	v_lshl_add_u64 v[0:1], s[2:3], 0, v[76:77]
	v_readlane_b32 s2, v248, 9
	v_cmp_le_i32_e32 vcc, v76, v114
	v_or_b32_e32 v3, 2, v76
	v_add_u32_e32 v78, s2, v114
; __device__ __forceinline__ unsigned pkbf(float lo, float hi) { typedef float f2_t __attribute__((ext_vector_type(2))); typedef __bf16 b2_t __attribute__((ext_vector_type(2))); f2_t v = {lo, hi}; b2_t b = __builtin_convertvector(v, b2_t); return __builtin_bit_cast(unsigned, b); }
; __device__ __forceinline__ float bflo(unsigned w) { return __uint_as_float(w << 16); }
; template <int PAR> __device__ __forceinline__ void attn_sub(const bf16* KS, const bf16* VT, const float* BTg, const float* gq, float sink2, int n, int ti, int hq, const u32x4 w0, const u32x4 w1, bf16* MIX, ss_t* ssb, int lane) {
;     const int fr = lane & 15, fq = lane >> 4; const int qi = 16 * ti + fr, tb = ti - PAR; const int tok = n * 128 + qi;
;     bf16x8 qf[2];
;     { float f0[8], f1[8]; float ss = 0.f;
; #pragma unroll
;       for (int e = 0; e < 4; ++e) { f0[2 * e] = bflo(w0[e]); f0[2 * e + 1] = bfhi(w0[e]); f1[2 * e] = bflo(w1[e]); f1[2 * e + 1] = bfhi(w1[e]);
;           ss += (f0[2 * e] * f0[2 * e] + f0[2 * e + 1] * f0[2 * e + 1]) + (f1[2 * e] * f1[2 * e] + f1[2 * e + 1] * f1[2 * e + 1]); }
;       ss += __shfl_xor(ss, 16); ss += __shfl_xor(ss, 32);
;       const float rs = (0.125f * 1.4426950408889634f) / sqrtf(ss * (1.0f / 64.f) + EPS);
;       const f32x4 a0 = *(const f32x4*)(gq + 8 * fq), a1 = *(const f32x4*)(gq + 8 * fq + 4), b0 = *(const f32x4*)(gq + 32 + 8 * fq), b1 = *(const f32x4*)(gq + 32 + 8 * fq + 4);
; __device__ __forceinline__ void mixer_phase256(const Args& A, int l, int vc, const bf16* Z, bf16* MIX, ss_t* ssa, ss_t* ssb, unsigned char* lds, int tid, int wid, int lane) {
;     ...
;     u32x2 uw[4][4];
; #pragma unroll
;     for (int j = 0; j < 4; ++j)
; #pragma unroll
;         for (int dt = 0; dt < 4; ++dt) uw[j][dt] = *(const u32x2*)(Z + (size_t)((cb + j) * 128 + st) * INW + h * 64 + 16 * dt + 4 * fq);
;     __syncthreads();
;     {
;         bf16x8 bfr[4];
; #pragma unroll
;         for (int ks = 0; ks < 4; ++ks) { float f[8] = {wa[ks][0].x, wa[ks][0].y, wa[ks][0].z, wa[ks][0].w, wa[ks][1].x, wa[ks][1].y, wa[ks][1].z, wa[ks][1].w}; const int s0 = 32 * ks + 8 * fq;
; #pragma unroll
;             for (int e = 0; e < 8; ++e) f[e] = (s0 + e <= st) ? f[e] : 0.f;
;             u32x4 w; w.x = pkbf(f[0], f[1]); w.y = pkbf(f[2], f[3]); w.z = pkbf(f[4], f[5]); w.w = pkbf(f[6], f[7]); bfr[ks] = __builtin_bit_cast(bf16x8, w); }
	v_mad_i64_i32 v[46:47], s[2:3], v78, s85, v[0:1]
	v_readlane_b32 s2, v248, 7
	global_load_dwordx2 v[86:87], v[46:47], off
	global_load_dwordx2 v[84:85], v[46:47], off offset:32
	global_load_dwordx2 v[82:83], v[46:47], off offset:64
	global_load_dwordx2 v[80:81], v[46:47], off offset:96
	v_add_u32_e32 v66, s2, v114
	v_mad_i64_i32 v[46:47], s[2:3], v66, s85, v[0:1]
	v_readlane_b32 s2, v248, 8
	global_load_dwordx2 v[74:75], v[46:47], off
	global_load_dwordx2 v[72:73], v[46:47], off offset:32
	global_load_dwordx2 v[70:71], v[46:47], off offset:64
	global_load_dwordx2 v[68:69], v[46:47], off offset:96
	v_add_u32_e32 v56, s2, v114
	v_mad_i64_i32 v[46:47], s[2:3], v56, s85, v[0:1]
	v_readlane_b32 s2, v248, 10
	global_load_dwordx2 v[64:65], v[46:47], off
	global_load_dwordx2 v[62:63], v[46:47], off offset:32
	global_load_dwordx2 v[60:61], v[46:47], off offset:64
	global_load_dwordx2 v[58:59], v[46:47], off offset:96
	v_add_u32_e32 v46, s2, v114
	v_mad_i64_i32 v[0:1], s[2:3], v46, s85, v[0:1]
	global_load_dwordx2 v[54:55], v[0:1], off
	global_load_dwordx2 v[52:53], v[0:1], off offset:32
	global_load_dwordx2 v[50:51], v[0:1], off offset:64
	global_load_dwordx2 v[48:49], v[0:1], off offset:96
	v_mov_b32_e32 v200, s73
	v_and_b32_e32 v201, 1, v200
	v_lshrrev_b32_e32 v200, 1, v200
	v_readlane_b32 s100, v249, 63
	v_and_b32_e32 v203, 15, v174
	v_lshl_add_u32 v203, v201, 6, v203
	v_add_u32_e32 v202, s100, v200
	v_readlane_b32 s100, v248, 1
	v_lshrrev_b32_e32 v200, 4, v174
	v_mov_b32_e32 v201, s78
	v_add_u32_e32 v203, s100, v203
	v_mul_u32_u24_e32 v251, 0x1c00, v203
	v_lshl_add_u32 v251, v202, 7, v251
	v_lshl_add_u32 v251, v200, 4, v251
	v_add_u32_e32 v251, 0x18201000, v251
	v_readlane_b32 s100, v250, 28
	v_readlane_b32 s101, v250, 29
	s_nop 4
	global_load_dwordx4 v[116:119], v251, s[100:101]
	global_load_dwordx4 v[120:123], v251, s[100:101] offset:64
	v_add_u32_e32 v251, 0x1c000, v251
	global_load_dwordx4 v[124:127], v251, s[100:101]
	global_load_dwordx4 v[128:131], v251, s[100:101] offset:64
	v_add_u32_e32 v251, 0x1c000, v251
	global_load_dwordx4 v[132:135], v251, s[100:101]
	global_load_dwordx4 v[136:139], v251, s[100:101] offset:64
	v_add_u32_e32 v251, 0x1c000, v251
	global_load_dwordx4 v[140:143], v251, s[100:101]
	global_load_dwordx4 v[144:147], v251, s[100:101] offset:64
	v_readlane_b32 s100, v250, 26
	v_readlane_b32 s101, v250, 27
	v_lshlrev_b32_e32 v203, 5, v200
	v_lshl_add_u32 v203, v201, 8, v203
	s_nop 2
	global_load_dwordx4 v[148:151], v203, s[100:101]
	global_load_dwordx4 v[152:155], v203, s[100:101] offset:16
	global_load_dwordx4 v[156:159], v203, s[100:101] offset:128
	global_load_dwordx4 v[180:183], v203, s[100:101] offset:144
	v_readlane_b32 s100, v250, 32
	v_readlane_b32 s101, v250, 33
	v_lshl_add_u32 v203, v201, 4, v202
	v_lshlrev_b32_e32 v203, 2, v203
	s_nop 2
	global_load_dword v184, v203, s[100:101]
	v_and_b32_e32 v96, 15, v174
	v_lshrrev_b32_e32 v97, 4, v174
	s_lshl_b32 s20, s73, 4
	v_add_u32_e32 v98, s20, v96
	v_lshlrev_b32_e32 v99, 3, v97
	v_sub_u32_e32 v99, v98, v99
	v_mov_b32_e32 v3, v99
	v_cmp_le_i32_e64 s[4:5], 0, v3
	v_cmp_le_i32_e64 s[6:7], 1, v3
	v_cmp_le_i32_e64 s[8:9], 2, v3
	v_cmp_le_i32_e64 s[10:11], 3, v3
	v_cmp_le_i32_e64 s[12:13], 4, v3
	v_cmp_le_i32_e64 s[14:15], 5, v3
	v_cmp_le_i32_e64 s[16:17], 6, v3
	v_cmp_le_i32_e64 s[18:19], 7, v3
	v_cndmask_b32_e64 v40, 0, v40, s[4:5]
	v_cndmask_b32_e64 v41, 0, v41, s[6:7]
	v_cndmask_b32_e64 v42, 0, v42, s[8:9]
	v_cndmask_b32_e64 v43, 0, v43, s[10:11]
	v_cndmask_b32_e64 v36, 0, v36, s[12:13]
	v_cndmask_b32_e64 v37, 0, v37, s[14:15]
	v_cndmask_b32_e64 v38, 0, v38, s[16:17]
	v_cndmask_b32_e64 v39, 0, v39, s[18:19]
	v_cvt_pk_bf16_f32 v4, v40, v41
	v_cvt_pk_bf16_f32 v5, v42, v43
	v_cvt_pk_bf16_f32 v6, v36, v37
	v_cvt_pk_bf16_f32 v7, v38, v39
	v_add_u32_e32 v3, 0xffffffe0, v99
	v_cmp_le_i32_e64 s[4:5], 0, v3
	v_cmp_le_i32_e64 s[6:7], 1, v3
	v_cmp_le_i32_e64 s[8:9], 2, v3
	v_cmp_le_i32_e64 s[10:11], 3, v3
	v_cmp_le_i32_e64 s[12:13], 4, v3
	v_cmp_le_i32_e64 s[14:15], 5, v3
	v_cmp_le_i32_e64 s[16:17], 6, v3
	v_cmp_le_i32_e64 s[18:19], 7, v3
	v_cndmask_b32_e64 v16, 0, v16, s[4:5]
	v_cndmask_b32_e64 v17, 0, v17, s[6:7]
	v_cndmask_b32_e64 v18, 0, v18, s[8:9]
	v_cndmask_b32_e64 v19, 0, v19, s[10:11]
	v_cndmask_b32_e64 v32, 0, v32, s[12:13]
	v_cndmask_b32_e64 v33, 0, v33, s[14:15]
	v_cndmask_b32_e64 v34, 0, v34, s[16:17]
	v_cndmask_b32_e64 v35, 0, v35, s[18:19]
	v_cvt_pk_bf16_f32 v8, v16, v17
	v_cvt_pk_bf16_f32 v9, v18, v19
	v_cvt_pk_bf16_f32 v10, v32, v33
	v_cvt_pk_bf16_f32 v11, v34, v35
	v_add_u32_e32 v3, 0xffffffc0, v99
	v_cmp_le_i32_e64 s[4:5], 0, v3
	v_cmp_le_i32_e64 s[6:7], 1, v3
	v_cmp_le_i32_e64 s[8:9], 2, v3
	v_cmp_le_i32_e64 s[10:11], 3, v3
	v_cmp_le_i32_e64 s[12:13], 4, v3
	v_cmp_le_i32_e64 s[14:15], 5, v3
	v_cmp_le_i32_e64 s[16:17], 6, v3
	v_cmp_le_i32_e64 s[18:19], 7, v3
	v_cndmask_b32_e64 v28, 0, v28, s[4:5]
	v_cndmask_b32_e64 v29, 0, v29, s[6:7]
	v_cndmask_b32_e64 v30, 0, v30, s[8:9]
	v_cndmask_b32_e64 v31, 0, v31, s[10:11]
	v_cndmask_b32_e64 v24, 0, v24, s[12:13]
	v_cndmask_b32_e64 v25, 0, v25, s[14:15]
	v_cndmask_b32_e64 v26, 0, v26, s[16:17]
	v_cndmask_b32_e64 v27, 0, v27, s[18:19]
	v_cvt_pk_bf16_f32 v88, v28, v29
	v_cvt_pk_bf16_f32 v89, v30, v31
	v_cvt_pk_bf16_f32 v90, v24, v25
	v_cvt_pk_bf16_f32 v91, v26, v27
	v_add_u32_e32 v3, 0xffffffa0, v99
	v_cmp_le_i32_e64 s[4:5], 0, v3
	v_cmp_le_i32_e64 s[6:7], 1, v3
	v_cmp_le_i32_e64 s[8:9], 2, v3
	v_cmp_le_i32_e64 s[10:11], 3, v3
	v_cmp_le_i32_e64 s[12:13], 4, v3
	v_cmp_le_i32_e64 s[14:15], 5, v3
	v_cmp_le_i32_e64 s[16:17], 6, v3
	v_cmp_le_i32_e64 s[18:19], 7, v3
	v_cndmask_b32_e64 v12, 0, v12, s[4:5]
	v_cndmask_b32_e64 v13, 0, v13, s[6:7]
	v_cndmask_b32_e64 v14, 0, v14, s[8:9]
	v_cndmask_b32_e64 v15, 0, v15, s[10:11]
	v_cndmask_b32_e64 v20, 0, v20, s[12:13]
	v_cndmask_b32_e64 v21, 0, v21, s[14:15]
	v_cndmask_b32_e64 v22, 0, v22, s[16:17]
	v_cndmask_b32_e64 v23, 0, v23, s[18:19]
	v_cvt_pk_bf16_f32 v92, v12, v13
	v_cvt_pk_bf16_f32 v93, v14, v15
	v_cvt_pk_bf16_f32 v94, v20, v21
	v_cvt_pk_bf16_f32 v95, v22, v23
	s_waitcnt lgkmcnt(0)
	s_barrier
; #define MFMA16(a, b, c) __builtin_amdgcn_mfma_f32_16x16x32_bf16((a), (b), (c), 0, 0, 0)
; __device__ __forceinline__ void mixer_phase256(const Args& A, int l, int vc, const bf16* Z, bf16* MIX, ss_t* ssa, ss_t* ssb, unsigned char* lds, int tid, int wid, int lane) {
;     ...
; #pragma unroll
;         for (int j = 0; j < 4; ++j) {
;             const bf16* vn = VN + j * 64 * VN_STRIDE; const size_t tok = (size_t)((cb + j) * 128 + st); float sq = 0.f;
; #pragma unroll
;             for (int dt = 0; dt < 4; ++dt) {
;                 f32x4 acc = (f32x4){0.f, 0.f, 0.f, 0.f};
; #pragma unroll
;                 for (int ks = 0; ks < 4; ++ks) if (ks < nks) { const bf16x8 a = *(const bf16x8*)(vn + (16 * dt + fr) * VN_STRIDE + 32 * ks + 8 * fq); acc = MFMA16(a, bfr[ks], acc); }
	v_readlane_b32 s100, v250, 28
	v_readlane_b32 s101, v250, 29
	v_readlane_b32 s21, v248, 6
	v_readlane_b32 s22, v248, 3
	s_lshr_b32 s23, s73, 1
	v_mul_u32_u24_e32 v100, 0x110, v96
	v_lshl_add_u32 v100, v97, 4, v100
	v_add_u32_e32 v100, 0x11c00, v100
	v_xor_b32_e32 v56, 16, v174
	v_lshlrev_b32_e32 v56, 2, v56
	v_xor_b32_e32 v57, 32, v174
	v_lshlrev_b32_e32 v57, 2, v57
	v_cmp_eq_u32_e64 s[24:25], 0, v97
	s_lshl_b32 s26, s21, 7
	v_add_u32_e32 v3, s26, v98
	v_lshlrev_b32_e32 v253, 12, v3
	s_lshl_b32 s26, s22, 7
	s_add_i32 s26, s26, 0x1ba00000
	v_add_u32_e32 v253, s26, v253
	v_lshl_add_u32 v253, v97, 3, v253
	s_add_i32 s26, s78, 9
	s_lshl_b32 s26, s26, 16
	v_lshl_add_u32 v254, v3, 3, s26
	ds_read_b128 v[12:15], v100 offset:0
	ds_read_b128 v[28:31], v100 offset:4352
	s_cmp_lt_u32 s23, 1
	s_cbranch_scc1 .Lsg2_r_0
	ds_read_b128 v[16:19], v100 offset:64
	ds_read_b128 v[32:35], v100 offset:4416
	s_cmp_lt_u32 s23, 2
	s_cbranch_scc1 .Lsg2_r_0
	ds_read_b128 v[20:23], v100 offset:128
	ds_read_b128 v[36:39], v100 offset:4480
	s_cmp_lt_u32 s23, 3
	s_cbranch_scc1 .Lsg2_r_0
	ds_read_b128 v[24:27], v100 offset:192
	ds_read_b128 v[40:43], v100 offset:4544

; __device__ __forceinline__ unsigned pkbf(float lo, float hi) { typedef float f2_t __attribute__((ext_vector_type(2))); typedef __bf16 b2_t __attribute__((ext_vector_type(2))); f2_t v = {lo, hi}; b2_t b = __builtin_convertvector(v, b2_t); return __builtin_bit_cast(unsigned, b); }
; __device__ __forceinline__ float bflo(unsigned w) { return __uint_as_float(w << 16); }
; __device__ __forceinline__ float bfhi(unsigned w) { return __uint_as_float(w & 0xffff0000u); }
; #define MFMA16(a, b, c) __builtin_amdgcn_mfma_f32_16x16x32_bf16((a), (b), (c), 0, 0, 0)
; __device__ __forceinline__ void mixer_phase256(const Args& A, int l, int vc, const bf16* Z, bf16* MIX, ss_t* ssa, ss_t* ssb, unsigned char* lds, int tid, int wid, int lane) {
;     ...
;         for (int j = 0; j < 4; ++j) {
;             const bf16* vn = VN + j * 64 * VN_STRIDE; const size_t tok = (size_t)((cb + j) * 128 + st); float sq = 0.f;
; #pragma unroll
;             for (int dt = 0; dt < 4; ++dt) {
;                 f32x4 acc = (f32x4){0.f, 0.f, 0.f, 0.f};
; #pragma unroll
;                 for (int ks = 0; ks < 4; ++ks) if (ks < nks) { const bf16x8 a = *(const bf16x8*)(vn + (16 * dt + fr) * VN_STRIDE + 32 * ks + 8 * fq); acc = MFMA16(a, bfr[ks], acc); }
;                 const float v0 = bflo(uw[j][dt].x) * (acc[0] + sbias), v1 = bfhi(uw[j][dt].x) * (acc[1] + sbias), v2 = bflo(uw[j][dt].y) * (acc[2] + sbias), v3 = bfhi(uw[j][dt].y) * (acc[3] + sbias);
;                 sq += (v0 * v0 + v1 * v1) + (v2 * v2 + v3 * v3);
;                 u32x2 w; w.x = pkbf(v0, v1); w.y = pkbf(v2, v3);
;                 *(u32x2*)(MIX + tok * DM + h * 64 + 16 * dt + 4 * fq) = w;
.Lsg2_m_1:
	s_waitcnt vmcnt(25)
	s_nop 3
	v_lshlrev_b32_e32 v96, 16, v86
	v_and_b32_e32 v97, 0xffff0000, v86
	v_lshlrev_b32_e32 v98, 16, v87
	v_and_b32_e32 v99, 0xffff0000, v87
	v_pk_add_f32 v[186:187], v[112:113], v[186:187] op_sel_hi:[0,1]
	v_pk_add_f32 v[188:189], v[112:113], v[188:189] op_sel_hi:[0,1]
	v_pk_mul_f32 v[186:187], v[96:97], v[186:187]
	v_pk_mul_f32 v[188:189], v[98:99], v[188:189]
	v_pk_mul_f32 v[202:203], v[186:187], v[186:187]
	v_pk_fma_f32 v[202:203], v[188:189], v[188:189], v[202:203]
	v_cvt_pk_bf16_f32 v0, v186, v187
	v_cvt_pk_bf16_f32 v1, v188, v189
	global_store_dwordx2 v253, v[0:1], s[100:101] offset:0
	v_lshlrev_b32_e32 v96, 16, v84
	v_and_b32_e32 v97, 0xffff0000, v84
	v_lshlrev_b32_e32 v98, 16, v85
	v_and_b32_e32 v99, 0xffff0000, v85
	v_pk_add_f32 v[190:191], v[112:113], v[190:191] op_sel_hi:[0,1]
	v_pk_add_f32 v[192:193], v[112:113], v[192:193] op_sel_hi:[0,1]
	v_pk_mul_f32 v[190:191], v[96:97], v[190:191]
	v_pk_mul_f32 v[192:193], v[98:99], v[192:193]
	v_pk_fma_f32 v[202:203], v[190:191], v[190:191], v[202:203]
	v_pk_fma_f32 v[202:203], v[192:193], v[192:193], v[202:203]
	v_cvt_pk_bf16_f32 v46, v190, v191
	v_cvt_pk_bf16_f32 v47, v192, v193
	global_store_dwordx2 v253, v[46:47], s[100:101] offset:32
	s_waitcnt lgkmcnt(0)
	ds_read_b128 v[212:215], v100 offset:26112
	ds_read_b128 v[228:231], v100 offset:30464
	s_cmp_lt_u32 s23, 1
	s_cbranch_scc1 .Lsg2_r_3
	ds_read_b128 v[216:219], v100 offset:26176
	ds_read_b128 v[232:235], v100 offset:30528
	s_cmp_lt_u32 s23, 2
	s_cbranch_scc1 .Lsg2_r_3
	ds_read_b128 v[220:223], v100 offset:26240
	ds_read_b128 v[236:239], v100 offset:30592
	s_cmp_lt_u32 s23, 3
	s_cbranch_scc1 .Lsg2_r_3
	ds_read_b128 v[224:227], v100 offset:26304
	ds_read_b128 v[240:243], v100 offset:30656

; __device__ __forceinline__ unsigned pkbf(float lo, float hi) { typedef float f2_t __attribute__((ext_vector_type(2))); typedef __bf16 b2_t __attribute__((ext_vector_type(2))); f2_t v = {lo, hi}; b2_t b = __builtin_convertvector(v, b2_t); return __builtin_bit_cast(unsigned, b); }
; __device__ __forceinline__ float bflo(unsigned w) { return __uint_as_float(w << 16); }
; __device__ __forceinline__ float bfhi(unsigned w) { return __uint_as_float(w & 0xffff0000u); }
; #define MFMA16(a, b, c) __builtin_amdgcn_mfma_f32_16x16x32_bf16((a), (b), (c), 0, 0, 0)
; __device__ __forceinline__ void mixer_phase256(const Args& A, int l, int vc, const bf16* Z, bf16* MIX, ss_t* ssa, ss_t* ssb, unsigned char* lds, int tid, int wid, int lane) {
;     ...
;         for (int j = 0; j < 4; ++j) {
;             const bf16* vn = VN + j * 64 * VN_STRIDE; const size_t tok = (size_t)((cb + j) * 128 + st); float sq = 0.f;
; #pragma unroll
;             for (int dt = 0; dt < 4; ++dt) {
;                 f32x4 acc = (f32x4){0.f, 0.f, 0.f, 0.f};
; #pragma unroll
;                 for (int ks = 0; ks < 4; ++ks) if (ks < nks) { const bf16x8 a = *(const bf16x8*)(vn + (16 * dt + fr) * VN_STRIDE + 32 * ks + 8 * fq); acc = MFMA16(a, bfr[ks], acc); }
;                 const float v0 = bflo(uw[j][dt].x) * (acc[0] + sbias), v1 = bfhi(uw[j][dt].x) * (acc[1] + sbias), v2 = bflo(uw[j][dt].y) * (acc[2] + sbias), v3 = bfhi(uw[j][dt].y) * (acc[3] + sbias);
;                 sq += (v0 * v0 + v1 * v1) + (v2 * v2 + v3 * v3);
;                 u32x2 w; w.x = pkbf(v0, v1); w.y = pkbf(v2, v3);
;                 *(u32x2*)(MIX + tok * DM + h * 64 + 16 * dt + 4 * fq) = w;
.Lsg2_m_3:
	s_waitcnt vmcnt(26)
	s_nop 3
	v_lshlrev_b32_e32 v96, 16, v74
	v_and_b32_e32 v97, 0xffff0000, v74
	v_lshlrev_b32_e32 v98, 16, v75
	v_and_b32_e32 v99, 0xffff0000, v75
	v_pk_add_f32 v[186:187], v[112:113], v[186:187] op_sel_hi:[0,1]
	v_pk_add_f32 v[188:189], v[112:113], v[188:189] op_sel_hi:[0,1]
	v_pk_mul_f32 v[186:187], v[96:97], v[186:187]
	v_pk_mul_f32 v[188:189], v[98:99], v[188:189]
	v_pk_mul_f32 v[202:203], v[186:187], v[186:187]
	v_pk_fma_f32 v[202:203], v[188:189], v[188:189], v[202:203]
	v_cvt_pk_bf16_f32 v0, v186, v187
	v_cvt_pk_bf16_f32 v1, v188, v189
	global_store_dwordx2 v253, v[0:1], s[100:101] offset:0
	v_lshlrev_b32_e32 v96, 16, v72
	v_and_b32_e32 v97, 0xffff0000, v72
	v_lshlrev_b32_e32 v98, 16, v73
	v_and_b32_e32 v99, 0xffff0000, v73
	v_pk_add_f32 v[190:191], v[112:113], v[190:191] op_sel_hi:[0,1]
	v_pk_add_f32 v[192:193], v[112:113], v[192:193] op_sel_hi:[0,1]
	v_pk_mul_f32 v[190:191], v[96:97], v[190:191]
	v_pk_mul_f32 v[192:193], v[98:99], v[192:193]
	v_pk_fma_f32 v[202:203], v[190:191], v[190:191], v[202:203]
	v_pk_fma_f32 v[202:203], v[192:193], v[192:193], v[202:203]
	v_cvt_pk_bf16_f32 v46, v190, v191
	v_cvt_pk_bf16_f32 v47, v192, v193
	global_store_dwordx2 v253, v[46:47], s[100:101] offset:32
	s_waitcnt lgkmcnt(0)
	ds_read_b128 v[212:215], v100 offset:43520
	ds_read_b128 v[228:231], v100 offset:47872
	s_cmp_lt_u32 s23, 1
	s_cbranch_scc1 .Lsg2_r_5
	ds_read_b128 v[216:219], v100 offset:43584
	ds_read_b128 v[232:235], v100 offset:47936
	s_cmp_lt_u32 s23, 2
	s_cbranch_scc1 .Lsg2_r_5
	ds_read_b128 v[220:223], v100 offset:43648
	ds_read_b128 v[236:239], v100 offset:48000
	s_cmp_lt_u32 s23, 3
	s_cbranch_scc1 .Lsg2_r_5
	ds_read_b128 v[224:227], v100 offset:43712
	ds_read_b128 v[240:243], v100 offset:48064

; __device__ __forceinline__ unsigned pkbf(float lo, float hi) { typedef float f2_t __attribute__((ext_vector_type(2))); typedef __bf16 b2_t __attribute__((ext_vector_type(2))); f2_t v = {lo, hi}; b2_t b = __builtin_convertvector(v, b2_t); return __builtin_bit_cast(unsigned, b); }
; __device__ __forceinline__ float bflo(unsigned w) { return __uint_as_float(w << 16); }
; __device__ __forceinline__ float bfhi(unsigned w) { return __uint_as_float(w & 0xffff0000u); }
; #define MFMA16(a, b, c) __builtin_amdgcn_mfma_f32_16x16x32_bf16((a), (b), (c), 0, 0, 0)
; __device__ __forceinline__ void mixer_phase256(const Args& A, int l, int vc, const bf16* Z, bf16* MIX, ss_t* ssa, ss_t* ssb, unsigned char* lds, int tid, int wid, int lane) {
;     ...
;         for (int j = 0; j < 4; ++j) {
;             const bf16* vn = VN + j * 64 * VN_STRIDE; const size_t tok = (size_t)((cb + j) * 128 + st); float sq = 0.f;
; #pragma unroll
;             for (int dt = 0; dt < 4; ++dt) {
;                 f32x4 acc = (f32x4){0.f, 0.f, 0.f, 0.f};
; #pragma unroll
;                 for (int ks = 0; ks < 4; ++ks) if (ks < nks) { const bf16x8 a = *(const bf16x8*)(vn + (16 * dt + fr) * VN_STRIDE + 32 * ks + 8 * fq); acc = MFMA16(a, bfr[ks], acc); }
;                 const float v0 = bflo(uw[j][dt].x) * (acc[0] + sbias), v1 = bfhi(uw[j][dt].x) * (acc[1] + sbias), v2 = bflo(uw[j][dt].y) * (acc[2] + sbias), v3 = bfhi(uw[j][dt].y) * (acc[3] + sbias);
;                 sq += (v0 * v0 + v1 * v1) + (v2 * v2 + v3 * v3);
;                 u32x2 w; w.x = pkbf(v0, v1); w.y = pkbf(v2, v3);
;                 *(u32x2*)(MIX + tok * DM + h * 64 + 16 * dt + 4 * fq) = w;
.Lsg2_m_5:
	s_waitcnt vmcnt(27)
	s_nop 3
	v_lshlrev_b32_e32 v96, 16, v64
	v_and_b32_e32 v97, 0xffff0000, v64
	v_lshlrev_b32_e32 v98, 16, v65
	v_and_b32_e32 v99, 0xffff0000, v65
	v_pk_add_f32 v[186:187], v[112:113], v[186:187] op_sel_hi:[0,1]
	v_pk_add_f32 v[188:189], v[112:113], v[188:189] op_sel_hi:[0,1]
	v_pk_mul_f32 v[186:187], v[96:97], v[186:187]
	v_pk_mul_f32 v[188:189], v[98:99], v[188:189]
	v_pk_mul_f32 v[202:203], v[186:187], v[186:187]
	v_pk_fma_f32 v[202:203], v[188:189], v[188:189], v[202:203]
	v_cvt_pk_bf16_f32 v0, v186, v187
	v_cvt_pk_bf16_f32 v1, v188, v189
	global_store_dwordx2 v253, v[0:1], s[100:101] offset:0
	v_lshlrev_b32_e32 v96, 16, v62
	v_and_b32_e32 v97, 0xffff0000, v62
	v_lshlrev_b32_e32 v98, 16, v63
	v_and_b32_e32 v99, 0xffff0000, v63
	v_pk_add_f32 v[190:191], v[112:113], v[190:191] op_sel_hi:[0,1]
	v_pk_add_f32 v[192:193], v[112:113], v[192:193] op_sel_hi:[0,1]
	v_pk_mul_f32 v[190:191], v[96:97], v[190:191]
	v_pk_mul_f32 v[192:193], v[98:99], v[192:193]
	v_pk_fma_f32 v[202:203], v[190:191], v[190:191], v[202:203]
	v_pk_fma_f32 v[202:203], v[192:193], v[192:193], v[202:203]
	v_cvt_pk_bf16_f32 v46, v190, v191
	v_cvt_pk_bf16_f32 v47, v192, v193
	global_store_dwordx2 v253, v[46:47], s[100:101] offset:32
	s_waitcnt lgkmcnt(0)
	ds_read_b128 v[212:215], v100 offset:60928
	ds_read_b128 v[228:231], v100 offset:65280
	s_cmp_lt_u32 s23, 1
	s_cbranch_scc1 .Lsg2_r_7
	ds_read_b128 v[216:219], v100 offset:60992
	ds_read_b128 v[232:235], v100 offset:65344
	s_cmp_lt_u32 s23, 2
	s_cbranch_scc1 .Lsg2_r_7
	ds_read_b128 v[220:223], v100 offset:61056
	ds_read_b128 v[236:239], v100 offset:65408
	s_cmp_lt_u32 s23, 3
	s_cbranch_scc1 .Lsg2_r_7
	ds_read_b128 v[224:227], v100 offset:61120
	ds_read_b128 v[240:243], v100 offset:65472

; __device__ __forceinline__ void ss_add(ss_t* p, float sq) { const float fl = floorf(sq); const unsigned hi = (unsigned)fl, lo = (unsigned)((sq - fl) * 4294967296.0f); atomicAdd(p, ((ss_t)hi << 32) | (ss_t)lo); }
; __device__ __forceinline__ unsigned pkbf(float lo, float hi) { typedef float f2_t __attribute__((ext_vector_type(2))); typedef __bf16 b2_t __attribute__((ext_vector_type(2))); f2_t v = {lo, hi}; b2_t b = __builtin_convertvector(v, b2_t); return __builtin_bit_cast(unsigned, b); }
; __device__ __forceinline__ float bflo(unsigned w) { return __uint_as_float(w << 16); }
; __device__ __forceinline__ float bfhi(unsigned w) { return __uint_as_float(w & 0xffff0000u); }
; #define MFMA16(a, b, c) __builtin_amdgcn_mfma_f32_16x16x32_bf16((a), (b), (c), 0, 0, 0)
; __device__ __forceinline__ void mixer_phase256(const Args& A, int l, int vc, const bf16* Z, bf16* MIX, ss_t* ssa, ss_t* ssb, unsigned char* lds, int tid, int wid, int lane) {
;     ...
;         for (int j = 0; j < 4; ++j) {
;             const bf16* vn = VN + j * 64 * VN_STRIDE; const size_t tok = (size_t)((cb + j) * 128 + st); float sq = 0.f;
; #pragma unroll
;             for (int dt = 0; dt < 4; ++dt) {
;                 f32x4 acc = (f32x4){0.f, 0.f, 0.f, 0.f};
; #pragma unroll
;                 for (int ks = 0; ks < 4; ++ks) if (ks < nks) { const bf16x8 a = *(const bf16x8*)(vn + (16 * dt + fr) * VN_STRIDE + 32 * ks + 8 * fq); acc = MFMA16(a, bfr[ks], acc); }
;                 const float v0 = bflo(uw[j][dt].x) * (acc[0] + sbias), v1 = bfhi(uw[j][dt].x) * (acc[1] + sbias), v2 = bflo(uw[j][dt].y) * (acc[2] + sbias), v3 = bfhi(uw[j][dt].y) * (acc[3] + sbias);
;                 sq += (v0 * v0 + v1 * v1) + (v2 * v2 + v3 * v3);
;                 u32x2 w; w.x = pkbf(v0, v1); w.y = pkbf(v2, v3);
;                 *(u32x2*)(MIX + tok * DM + h * 64 + 16 * dt + 4 * fq) = w;
;             }
;             sq += __shfl_xor(sq, 16); sq += __shfl_xor(sq, 32); if (fq == 0) ss_add(ssa + tok, sq);
.Lsg2_m_7:
	s_waitcnt vmcnt(28)
	s_nop 3
	v_lshlrev_b32_e32 v96, 16, v54
	v_and_b32_e32 v97, 0xffff0000, v54
	v_lshlrev_b32_e32 v98, 16, v55
	v_and_b32_e32 v99, 0xffff0000, v55
	v_pk_add_f32 v[186:187], v[112:113], v[186:187] op_sel_hi:[0,1]
	v_pk_add_f32 v[188:189], v[112:113], v[188:189] op_sel_hi:[0,1]
	v_pk_mul_f32 v[186:187], v[96:97], v[186:187]
	v_pk_mul_f32 v[188:189], v[98:99], v[188:189]
	v_pk_mul_f32 v[202:203], v[186:187], v[186:187]
	v_pk_fma_f32 v[202:203], v[188:189], v[188:189], v[202:203]
	v_cvt_pk_bf16_f32 v0, v186, v187
	v_cvt_pk_bf16_f32 v1, v188, v189
	global_store_dwordx2 v253, v[0:1], s[100:101] offset:0
	v_lshlrev_b32_e32 v96, 16, v52
	v_and_b32_e32 v97, 0xffff0000, v52
	v_lshlrev_b32_e32 v98, 16, v53
	v_and_b32_e32 v99, 0xffff0000, v53
	v_pk_add_f32 v[190:191], v[112:113], v[190:191] op_sel_hi:[0,1]
	v_pk_add_f32 v[192:193], v[112:113], v[192:193] op_sel_hi:[0,1]
	v_pk_mul_f32 v[190:191], v[96:97], v[190:191]
	v_pk_mul_f32 v[192:193], v[98:99], v[192:193]
	v_pk_fma_f32 v[202:203], v[190:191], v[190:191], v[202:203]
	v_pk_fma_f32 v[202:203], v[192:193], v[192:193], v[202:203]
	v_cvt_pk_bf16_f32 v46, v190, v191
	v_cvt_pk_bf16_f32 v47, v192, v193
	global_store_dwordx2 v253, v[46:47], s[100:101] offset:32
	s_nop 7
	s_nop 0
	v_lshlrev_b32_e32 v96, 16, v50
	v_and_b32_e32 v97, 0xffff0000, v50
	v_lshlrev_b32_e32 v98, 16, v51
	v_and_b32_e32 v99, 0xffff0000, v51
	v_pk_add_f32 v[194:195], v[112:113], v[194:195] op_sel_hi:[0,1]
	v_pk_add_f32 v[196:197], v[112:113], v[196:197] op_sel_hi:[0,1]
	v_pk_mul_f32 v[194:195], v[96:97], v[194:195]
	v_pk_mul_f32 v[196:197], v[98:99], v[196:197]
	v_pk_fma_f32 v[202:203], v[194:195], v[194:195], v[202:203]
	v_pk_fma_f32 v[202:203], v[196:197], v[196:197], v[202:203]
	v_cvt_pk_bf16_f32 v0, v194, v195
	v_cvt_pk_bf16_f32 v1, v196, v197
	global_store_dwordx2 v253, v[0:1], s[100:101] offset:64
	v_lshlrev_b32_e32 v96, 16, v48
	v_and_b32_e32 v97, 0xffff0000, v48
	v_lshlrev_b32_e32 v98, 16, v49
	v_and_b32_e32 v99, 0xffff0000, v49
	v_pk_add_f32 v[198:199], v[112:113], v[198:199] op_sel_hi:[0,1]
	v_pk_add_f32 v[200:201], v[112:113], v[200:201] op_sel_hi:[0,1]
	v_pk_mul_f32 v[198:199], v[96:97], v[198:199]
	v_pk_mul_f32 v[200:201], v[98:99], v[200:201]
	v_pk_fma_f32 v[202:203], v[198:199], v[198:199], v[202:203]
	v_pk_fma_f32 v[202:203], v[200:201], v[200:201], v[202:203]
	v_cvt_pk_bf16_f32 v46, v198, v199
	v_cvt_pk_bf16_f32 v47, v200, v201
	global_store_dwordx2 v253, v[46:47], s[100:101] offset:96
	v_add_f32_e32 v3, v202, v203
	ds_bpermute_b32 v45, v56, v3
	s_waitcnt lgkmcnt(0)
	v_add_f32_e32 v3, v3, v45
	ds_bpermute_b32 v45, v57, v3
	s_waitcnt lgkmcnt(0)
	v_add_f32_e32 v3, v3, v45
	s_mov_b64 exec, s[24:25]
	v_floor_f32_e32 v45, v3
	v_sub_f32_e32 v3, v3, v45
	v_mul_f32_e32 v3, 0x4f800000, v3
	v_cvt_u32_f32_e32 v79, v45
	v_cvt_u32_f32_e32 v78, v3
	global_atomic_add_x2 v254, v[78:79], s[100:101] offset:3072
	s_mov_b64 exec, -1
	s_branch .Lsg2_done

; __device__ __forceinline__ unsigned pkbf(float lo, float hi) { typedef float f2_t __attribute__((ext_vector_type(2))); typedef __bf16 b2_t __attribute__((ext_vector_type(2))); f2_t v = {lo, hi}; b2_t b = __builtin_convertvector(v, b2_t); return __builtin_bit_cast(unsigned, b); }
; __device__ __forceinline__ float bflo(unsigned w) { return __uint_as_float(w << 16); }
; __device__ __forceinline__ float bfhi(unsigned w) { return __uint_as_float(w & 0xffff0000u); }
; template <int PAR> __device__ __forceinline__ void attn_sub(const bf16* KS, const bf16* VT, const float* BTg, const float* gq, float sink2, int n, int ti, int hq, const u32x4 w0, const u32x4 w1, bf16* MIX, ss_t* ssb, int lane) {
;     const int fr = lane & 15, fq = lane >> 4; const int qi = 16 * ti + fr, tb = ti - PAR; const int tok = n * 128 + qi;
;     bf16x8 qf[2];
;     { float f0[8], f1[8]; float ss = 0.f;
; #pragma unroll
;       for (int e = 0; e < 4; ++e) { f0[2 * e] = bflo(w0[e]); f0[2 * e + 1] = bfhi(w0[e]); f1[2 * e] = bflo(w1[e]); f1[2 * e + 1] = bfhi(w1[e]);
;           ss += (f0[2 * e] * f0[2 * e] + f0[2 * e + 1] * f0[2 * e + 1]) + (f1[2 * e] * f1[2 * e] + f1[2 * e + 1] * f1[2 * e + 1]); }
;       ss += __shfl_xor(ss, 16); ss += __shfl_xor(ss, 32);
;       const float rs = (0.125f * 1.4426950408889634f) / sqrtf(ss * (1.0f / 64.f) + EPS);
;       const f32x4 a0 = *(const f32x4*)(gq + 8 * fq), a1 = *(const f32x4*)(gq + 8 * fq + 4), b0 = *(const f32x4*)(gq + 32 + 8 * fq), b1 = *(const f32x4*)(gq + 32 + 8 * fq + 4);
;       u32x4 p0, p1;
;       p0.x = pkbf(f0[0] * rs * a0.x, f0[1] * rs * a0.y); p0.y = pkbf(f0[2] * rs * a0.z, f0[3] * rs * a0.w); p0.z = pkbf(f0[4] * rs * a1.x, f0[5] * rs * a1.y); p0.w = pkbf(f0[6] * rs * a1.z, f0[7] * rs * a1.w);
;       p1.x = pkbf(f1[0] * rs * b0.x, f1[1] * rs * b0.y); p1.y = pkbf(f1[2] * rs * b0.z, f1[3] * rs * b0.w); p1.z = pkbf(f1[4] * rs * b1.x, f1[5] * rs * b1.y); p1.w = pkbf(f1[6] * rs * b1.z, f1[7] * rs * b1.w);
;       qf[0] = __builtin_bit_cast(bf16x8, p0); qf[1] = __builtin_bit_cast(bf16x8, p1); }
;     const int e0 = 4 * fq - fr;
;     const float* bp = BTg + (128 - 16 * 8 - 3 - e0);
.Lsg2_done:
	s_waitcnt vmcnt(20)
	v_readlane_b32 s100, v250, 28
	v_readlane_b32 s101, v250, 29
	v_readlane_b32 s24, v249, 63
	v_readlane_b32 s23, v248, 1
	s_lshr_b32 s20, s73, 1
	s_and_b32 s21, s73, 1
	s_lshl_b32 s26, s21, 2
	v_and_b32_e32 v200, 15, v174
	v_lshrrev_b32_e32 v201, 4, v174
	s_add_i32 s22, s24, s20
	s_cmp_gt_i32 s23, 0
	s_cselect_b64 s[36:37], -1, 0
	v_lshlrev_b32_e32 v202, 2, v201
	v_add_u32_e32 v203, 0, v202
	v_cmp_gt_i32_e64 s[40:41], v203, v200
	v_add_u32_e32 v203, 1, v202
	v_cmp_gt_i32_e64 s[42:43], v203, v200
	v_add_u32_e32 v203, 2, v202
	v_cmp_gt_i32_e64 s[44:45], v203, v200
	v_add_u32_e32 v203, 3, v202
	v_cmp_gt_i32_e64 s[46:47], v203, v200
	v_cmp_eq_u32_e64 s[56:57], 0, v201
	v_mov_b32_e32 v203, s21
	v_lshl_add_u32 v185, v203, 6, v200
	v_mul_u32_u24_e32 v185, 0x90, v185
	v_lshl_add_u32 v185, v201, 4, v185
	v_lshlrev_b32_e32 v186, 2, v200
	v_lshlrev_b32_e32 v0, 4, v201
	v_sub_u32_e32 v186, v186, v0
	s_lshl_b32 s27, s20, 9
	s_add_i32 s27, s27, 0x113f4
	v_add_u32_e32 v186, s27, v186
	v_mul_u32_u24_e32 v187, 0x210, v200
	v_lshl_add_u32 v187, v203, 7, v187
	v_lshl_add_u32 v187, v201, 3, v187
	v_add_u32_e32 v187, 0x9000, v187
	v_add_u32_e32 v188, 0x2100, v187
	v_add_u32_e32 v189, 0x4200, v187
	v_add_u32_e32 v190, 0x6300, v187
	v_lshl_add_u32 v0, v203, 6, v200
	v_add_u32_e32 v0, s23, v0
	v_lshlrev_b32_e32 v191, 12, v0
	s_lshl_b32 s27, s22, 7
	s_add_i32 s27, s27, 0x1ba00800
	v_add_u32_e32 v191, s27, v191
	v_lshl_add_u32 v191, v201, 3, v191
	s_add_i32 s27, s78, 13
	s_lshl_b32 s27, s27, 16
	v_lshl_add_u32 v192, v0, 3, s27
	v_xor_b32_e32 v193, 16, v174
	v_lshlrev_b32_e32 v193, 2, v193
	v_xor_b32_e32 v194, 32, v174
	v_lshlrev_b32_e32 v194, 2, v194
	v_mov_b32_e32 v195, 0xf149f2ca
	v_mul_f32_e32 v184, 0x3fb8aa3b, v184
	v_lshlrev_b32_e32 v4, 16, v116
	v_and_b32_e32 v5, 0xffff0000, v116
	v_lshlrev_b32_e32 v6, 16, v117
	v_and_b32_e32 v7, 0xffff0000, v117
	v_lshlrev_b32_e32 v8, 16, v118
	v_and_b32_e32 v9, 0xffff0000, v118
	v_lshlrev_b32_e32 v10, 16, v119
	v_and_b32_e32 v11, 0xffff0000, v119
	v_lshlrev_b32_e32 v12, 16, v120
	v_and_b32_e32 v13, 0xffff0000, v120
	v_lshlrev_b32_e32 v14, 16, v121
	v_and_b32_e32 v15, 0xffff0000, v121
	v_lshlrev_b32_e32 v16, 16, v122
	v_and_b32_e32 v17, 0xffff0000, v122
	v_lshlrev_b32_e32 v18, 16, v123
	v_and_b32_e32 v19, 0xffff0000, v123
	v_pk_mul_f32 v[78:79], v[4:5], v[4:5]
	v_pk_fma_f32 v[78:79], v[6:7], v[6:7], v[78:79]
	v_pk_fma_f32 v[78:79], v[8:9], v[8:9], v[78:79]
	v_pk_fma_f32 v[78:79], v[10:11], v[10:11], v[78:79]
	v_pk_fma_f32 v[78:79], v[12:13], v[12:13], v[78:79]
	v_pk_fma_f32 v[78:79], v[14:15], v[14:15], v[78:79]
	v_pk_fma_f32 v[78:79], v[16:17], v[16:17], v[78:79]
	v_pk_fma_f32 v[78:79], v[18:19], v[18:19], v[78:79]
	v_add_f32_e32 v45, v78, v79
	v_lshlrev_b32_e32 v20, 16, v124
	v_and_b32_e32 v21, 0xffff0000, v124
	v_lshlrev_b32_e32 v22, 16, v125
	v_and_b32_e32 v23, 0xffff0000, v125
	v_lshlrev_b32_e32 v24, 16, v126
	v_and_b32_e32 v25, 0xffff0000, v126
	v_lshlrev_b32_e32 v26, 16, v127
	v_and_b32_e32 v27, 0xffff0000, v127
	v_lshlrev_b32_e32 v28, 16, v128
	v_and_b32_e32 v29, 0xffff0000, v128
	v_lshlrev_b32_e32 v30, 16, v129
	v_and_b32_e32 v31, 0xffff0000, v129
	v_lshlrev_b32_e32 v32, 16, v130
	v_and_b32_e32 v33, 0xffff0000, v130
	v_lshlrev_b32_e32 v34, 16, v131
	v_and_b32_e32 v35, 0xffff0000, v131
	v_pk_mul_f32 v[80:81], v[20:21], v[20:21]
	v_pk_fma_f32 v[80:81], v[22:23], v[22:23], v[80:81]
	v_pk_fma_f32 v[80:81], v[24:25], v[24:25], v[80:81]
	v_pk_fma_f32 v[80:81], v[26:27], v[26:27], v[80:81]
	v_pk_fma_f32 v[80:81], v[28:29], v[28:29], v[80:81]
	v_pk_fma_f32 v[80:81], v[30:31], v[30:31], v[80:81]
	v_pk_fma_f32 v[80:81], v[32:33], v[32:33], v[80:81]
	v_pk_fma_f32 v[80:81], v[34:35], v[34:35], v[80:81]
	v_add_f32_e32 v46, v80, v81
	v_lshlrev_b32_e32 v212, 16, v132
	v_and_b32_e32 v213, 0xffff0000, v132
	v_lshlrev_b32_e32 v214, 16, v133
	v_and_b32_e32 v215, 0xffff0000, v133
	v_lshlrev_b32_e32 v216, 16, v134
	v_and_b32_e32 v217, 0xffff0000, v134
	v_lshlrev_b32_e32 v218, 16, v135
	v_and_b32_e32 v219, 0xffff0000, v135
	v_lshlrev_b32_e32 v220, 16, v136
	v_and_b32_e32 v221, 0xffff0000, v136
	v_lshlrev_b32_e32 v222, 16, v137
	v_and_b32_e32 v223, 0xffff0000, v137
	v_lshlrev_b32_e32 v224, 16, v138
	v_and_b32_e32 v225, 0xffff0000, v138
	v_lshlrev_b32_e32 v226, 16, v139
	v_and_b32_e32 v227, 0xffff0000, v139
	v_pk_mul_f32 v[96:97], v[212:213], v[212:213]
	v_pk_fma_f32 v[96:97], v[214:215], v[214:215], v[96:97]
	v_pk_fma_f32 v[96:97], v[216:217], v[216:217], v[96:97]
	v_pk_fma_f32 v[96:97], v[218:219], v[218:219], v[96:97]
	v_pk_fma_f32 v[96:97], v[220:221], v[220:221], v[96:97]
	v_pk_fma_f32 v[96:97], v[222:223], v[222:223], v[96:97]
	v_pk_fma_f32 v[96:97], v[224:225], v[224:225], v[96:97]
	v_pk_fma_f32 v[96:97], v[226:227], v[226:227], v[96:97]
	v_add_f32_e32 v47, v96, v97
	v_lshlrev_b32_e32 v228, 16, v140
	v_and_b32_e32 v229, 0xffff0000, v140
	v_lshlrev_b32_e32 v230, 16, v141
	v_and_b32_e32 v231, 0xffff0000, v141
	v_lshlrev_b32_e32 v232, 16, v142
	v_and_b32_e32 v233, 0xffff0000, v142
	v_lshlrev_b32_e32 v234, 16, v143
	v_and_b32_e32 v235, 0xffff0000, v143
	v_lshlrev_b32_e32 v236, 16, v144
	v_and_b32_e32 v237, 0xffff0000, v144
	v_lshlrev_b32_e32 v238, 16, v145
	v_and_b32_e32 v239, 0xffff0000, v145
	v_lshlrev_b32_e32 v240, 16, v146
	v_and_b32_e32 v241, 0xffff0000, v146
	v_lshlrev_b32_e32 v242, 16, v147
	v_and_b32_e32 v243, 0xffff0000, v147
	v_pk_mul_f32 v[98:99], v[228:229], v[228:229]
	v_pk_fma_f32 v[98:99], v[230:231], v[230:231], v[98:99]
	v_pk_fma_f32 v[98:99], v[232:233], v[232:233], v[98:99]
	v_pk_fma_f32 v[98:99], v[234:235], v[234:235], v[98:99]
	v_pk_fma_f32 v[98:99], v[236:237], v[236:237], v[98:99]
	v_pk_fma_f32 v[98:99], v[238:239], v[238:239], v[98:99]
	v_pk_fma_f32 v[98:99], v[240:241], v[240:241], v[98:99]
	v_pk_fma_f32 v[98:99], v[242:243], v[242:243], v[98:99]
	v_add_f32_e32 v76, v98, v99
	ds_bpermute_b32 v0, v193, v45
	ds_bpermute_b32 v1, v193, v46
	ds_bpermute_b32 v3, v193, v47
	ds_bpermute_b32 v100, v193, v76
	s_waitcnt lgkmcnt(0)
; __device__ __forceinline__ unsigned pkbf(float lo, float hi) { typedef float f2_t __attribute__((ext_vector_type(2))); typedef __bf16 b2_t __attribute__((ext_vector_type(2))); f2_t v = {lo, hi}; b2_t b = __builtin_convertvector(v, b2_t); return __builtin_bit_cast(unsigned, b); }
; template <int PAR> __device__ __forceinline__ void attn_sub(const bf16* KS, const bf16* VT, const float* BTg, const float* gq, float sink2, int n, int ti, int hq, const u32x4 w0, const u32x4 w1, bf16* MIX, ss_t* ssb, int lane) {
;     ...
;       ss += __shfl_xor(ss, 16); ss += __shfl_xor(ss, 32);
;       const float rs = (0.125f * 1.4426950408889634f) / sqrtf(ss * (1.0f / 64.f) + EPS);
;       const f32x4 a0 = *(const f32x4*)(gq + 8 * fq), a1 = *(const f32x4*)(gq + 8 * fq + 4), b0 = *(const f32x4*)(gq + 32 + 8 * fq), b1 = *(const f32x4*)(gq + 32 + 8 * fq + 4);
;       u32x4 p0, p1;
;       p0.x = pkbf(f0[0] * rs * a0.x, f0[1] * rs * a0.y); p0.y = pkbf(f0[2] * rs * a0.z, f0[3] * rs * a0.w); p0.z = pkbf(f0[4] * rs * a1.x, f0[5] * rs * a1.y); p0.w = pkbf(f0[6] * rs * a1.z, f0[7] * rs * a1.w);
;       p1.x = pkbf(f1[0] * rs * b0.x, f1[1] * rs * b0.y); p1.y = pkbf(f1[2] * rs * b0.z, f1[3] * rs * b0.w); p1.z = pkbf(f1[4] * rs * b1.x, f1[5] * rs * b1.y); p1.w = pkbf(f1[6] * rs * b1.z, f1[7] * rs * b1.w);
;       qf[0] = __builtin_bit_cast(bf16x8, p0); qf[1] = __builtin_bit_cast(bf16x8, p1); }
;     const int e0 = 4 * fq - fr;
;     const float* bp = BTg + (128 - 16 * 8 - 3 - e0);
;     ...
;             const float v = valid ? acc[r] + bp[16 * (8 - rel) + (3 - r)] : -1e30f; acc[r] = v; mx = fmaxf(mx, v); }
	v_add_f32_e32 v45, v45, v0
	v_add_f32_e32 v46, v46, v1
	v_add_f32_e32 v47, v47, v3
	v_add_f32_e32 v76, v76, v100
	ds_bpermute_b32 v0, v194, v45
	ds_bpermute_b32 v1, v194, v46
	ds_bpermute_b32 v3, v194, v47
	ds_bpermute_b32 v100, v194, v76
	s_waitcnt lgkmcnt(0)
	v_add_f32_e32 v45, v45, v0
	v_add_f32_e32 v46, v46, v1
	v_add_f32_e32 v47, v47, v3
	v_add_f32_e32 v76, v76, v100
	v_fmamk_f32 v45, v45, 0x3c800000, v205
	v_fmamk_f32 v46, v46, 0x3c800000, v205
	v_fmamk_f32 v47, v47, 0x3c800000, v205
	v_fmamk_f32 v76, v76, 0x3c800000, v205
	v_rsq_f32_e32 v45, v45
	v_rsq_f32_e32 v46, v46
	v_rsq_f32_e32 v47, v47
	v_rsq_f32_e32 v76, v76
	s_nop 0
	v_mul_f32_e32 v78, 0x3e38aa3b, v45
	v_mul_f32_e32 v80, 0x3e38aa3b, v46
	v_mul_f32_e32 v96, 0x3e38aa3b, v47
	v_mul_f32_e32 v98, 0x3e38aa3b, v76
	v_pk_mul_f32 v[4:5], v[78:79], v[4:5] op_sel_hi:[0,1]
	v_pk_mul_f32 v[4:5], v[4:5], v[148:149]
	v_cvt_pk_bf16_f32 v116, v4, v5
	v_pk_mul_f32 v[6:7], v[78:79], v[6:7] op_sel_hi:[0,1]
	v_pk_mul_f32 v[6:7], v[6:7], v[150:151]
	v_cvt_pk_bf16_f32 v117, v6, v7
	v_pk_mul_f32 v[8:9], v[78:79], v[8:9] op_sel_hi:[0,1]
	v_pk_mul_f32 v[8:9], v[8:9], v[152:153]
	v_cvt_pk_bf16_f32 v118, v8, v9
	v_pk_mul_f32 v[10:11], v[78:79], v[10:11] op_sel_hi:[0,1]
	v_pk_mul_f32 v[10:11], v[10:11], v[154:155]
	v_cvt_pk_bf16_f32 v119, v10, v11
	v_pk_mul_f32 v[12:13], v[78:79], v[12:13] op_sel_hi:[0,1]
	v_pk_mul_f32 v[12:13], v[12:13], v[156:157]
	v_cvt_pk_bf16_f32 v120, v12, v13
	v_pk_mul_f32 v[14:15], v[78:79], v[14:15] op_sel_hi:[0,1]
	v_pk_mul_f32 v[14:15], v[14:15], v[158:159]
	v_cvt_pk_bf16_f32 v121, v14, v15
	v_pk_mul_f32 v[16:17], v[78:79], v[16:17] op_sel_hi:[0,1]
	v_pk_mul_f32 v[16:17], v[16:17], v[180:181]
	v_cvt_pk_bf16_f32 v122, v16, v17
	v_pk_mul_f32 v[18:19], v[78:79], v[18:19] op_sel_hi:[0,1]
	v_pk_mul_f32 v[18:19], v[18:19], v[182:183]
	v_cvt_pk_bf16_f32 v123, v18, v19
	v_pk_mul_f32 v[20:21], v[80:81], v[20:21] op_sel_hi:[0,1]
	v_pk_mul_f32 v[20:21], v[20:21], v[148:149]
	v_cvt_pk_bf16_f32 v124, v20, v21
	v_pk_mul_f32 v[22:23], v[80:81], v[22:23] op_sel_hi:[0,1]
	v_pk_mul_f32 v[22:23], v[22:23], v[150:151]
	v_cvt_pk_bf16_f32 v125, v22, v23
	v_pk_mul_f32 v[24:25], v[80:81], v[24:25] op_sel_hi:[0,1]
	v_pk_mul_f32 v[24:25], v[24:25], v[152:153]
	v_cvt_pk_bf16_f32 v126, v24, v25
	v_pk_mul_f32 v[26:27], v[80:81], v[26:27] op_sel_hi:[0,1]
	v_pk_mul_f32 v[26:27], v[26:27], v[154:155]
	v_cvt_pk_bf16_f32 v127, v26, v27
	v_pk_mul_f32 v[28:29], v[80:81], v[28:29] op_sel_hi:[0,1]
	v_pk_mul_f32 v[28:29], v[28:29], v[156:157]
	v_cvt_pk_bf16_f32 v128, v28, v29
	v_pk_mul_f32 v[30:31], v[80:81], v[30:31] op_sel_hi:[0,1]
	v_pk_mul_f32 v[30:31], v[30:31], v[158:159]
	v_cvt_pk_bf16_f32 v129, v30, v31
	v_pk_mul_f32 v[32:33], v[80:81], v[32:33] op_sel_hi:[0,1]
	v_pk_mul_f32 v[32:33], v[32:33], v[180:181]
	v_cvt_pk_bf16_f32 v130, v32, v33
	v_pk_mul_f32 v[34:35], v[80:81], v[34:35] op_sel_hi:[0,1]
	v_pk_mul_f32 v[34:35], v[34:35], v[182:183]
	v_cvt_pk_bf16_f32 v131, v34, v35
	v_pk_mul_f32 v[212:213], v[96:97], v[212:213] op_sel_hi:[0,1]
	v_pk_mul_f32 v[212:213], v[212:213], v[148:149]
	v_cvt_pk_bf16_f32 v132, v212, v213
	v_pk_mul_f32 v[214:215], v[96:97], v[214:215] op_sel_hi:[0,1]
	v_pk_mul_f32 v[214:215], v[214:215], v[150:151]
	v_cvt_pk_bf16_f32 v133, v214, v215
	v_pk_mul_f32 v[216:217], v[96:97], v[216:217] op_sel_hi:[0,1]
	v_pk_mul_f32 v[216:217], v[216:217], v[152:153]
	v_cvt_pk_bf16_f32 v134, v216, v217
	v_pk_mul_f32 v[218:219], v[96:97], v[218:219] op_sel_hi:[0,1]
	v_pk_mul_f32 v[218:219], v[218:219], v[154:155]
	v_cvt_pk_bf16_f32 v135, v218, v219
	v_pk_mul_f32 v[220:221], v[96:97], v[220:221] op_sel_hi:[0,1]
	v_pk_mul_f32 v[220:221], v[220:221], v[156:157]
	v_cvt_pk_bf16_f32 v136, v220, v221
	v_pk_mul_f32 v[222:223], v[96:97], v[222:223] op_sel_hi:[0,1]
	v_pk_mul_f32 v[222:223], v[222:223], v[158:159]
	v_cvt_pk_bf16_f32 v137, v222, v223
	v_pk_mul_f32 v[224:225], v[96:97], v[224:225] op_sel_hi:[0,1]
	v_pk_mul_f32 v[224:225], v[224:225], v[180:181]
	v_cvt_pk_bf16_f32 v138, v224, v225
	v_pk_mul_f32 v[226:227], v[96:97], v[226:227] op_sel_hi:[0,1]
	v_pk_mul_f32 v[226:227], v[226:227], v[182:183]
	v_cvt_pk_bf16_f32 v139, v226, v227
	v_pk_mul_f32 v[228:229], v[98:99], v[228:229] op_sel_hi:[0,1]
	v_pk_mul_f32 v[228:229], v[228:229], v[148:149]
	v_cvt_pk_bf16_f32 v140, v228, v229
	v_pk_mul_f32 v[230:231], v[98:99], v[230:231] op_sel_hi:[0,1]
	v_pk_mul_f32 v[230:231], v[230:231], v[150:151]
	v_cvt_pk_bf16_f32 v141, v230, v231
	v_pk_mul_f32 v[232:233], v[98:99], v[232:233] op_sel_hi:[0,1]
	v_pk_mul_f32 v[232:233], v[232:233], v[152:153]
	v_cvt_pk_bf16_f32 v142, v232, v233
	v_pk_mul_f32 v[234:235], v[98:99], v[234:235] op_sel_hi:[0,1]
	v_pk_mul_f32 v[234:235], v[234:235], v[154:155]
	v_cvt_pk_bf16_f32 v143, v234, v235
	v_pk_mul_f32 v[236:237], v[98:99], v[236:237] op_sel_hi:[0,1]
	v_pk_mul_f32 v[236:237], v[236:237], v[156:157]
	v_cvt_pk_bf16_f32 v144, v236, v237
	v_pk_mul_f32 v[238:239], v[98:99], v[238:239] op_sel_hi:[0,1]
	v_pk_mul_f32 v[238:239], v[238:239], v[158:159]
	v_cvt_pk_bf16_f32 v145, v238, v239
	v_pk_mul_f32 v[240:241], v[98:99], v[240:241] op_sel_hi:[0,1]
	v_pk_mul_f32 v[240:241], v[240:241], v[180:181]
	v_cvt_pk_bf16_f32 v146, v240, v241
	v_pk_mul_f32 v[242:243], v[98:99], v[242:243] op_sel_hi:[0,1]
	v_pk_mul_f32 v[242:243], v[242:243], v[182:183]
	v_cvt_pk_bf16_f32 v147, v242, v243
	ds_read2_b32 v[84:85], v186 offset0:131 offset1:130
	ds_read2_b32 v[86:87], v186 offset0:129 offset1:128
	ds_read2_b32 v[88:89], v186 offset0:115 offset1:114
	ds_read2_b32 v[90:91], v186 offset0:113 offset1:112
	ds_read2_b32 v[92:93], v186 offset0:99 offset1:98
	ds_read2_b32 v[94:95], v186 offset0:97 offset1:96
	ds_read2_b32 v[96:97], v186 offset0:83 offset1:82
	ds_read2_b32 v[98:99], v186 offset0:81 offset1:80
	ds_read2_b32 v[40:41], v186 offset0:67 offset1:66
	ds_read2_b32 v[42:43], v186 offset0:65 offset1:64
	s_waitcnt lgkmcnt(0)
; #define MFMA16(a, b, c) __builtin_amdgcn_mfma_f32_16x16x32_bf16((a), (b), (c), 0, 0, 0)
; template <int PAR> __device__ __forceinline__ void attn_sub(const bf16* KS, const bf16* VT, const float* BTg, const float* gq, float sink2, int n, int ti, int hq, const u32x4 w0, const u32x4 w1, bf16* MIX, ss_t* ssb, int lane) {
;     ...
;     for (int t = 0; t < 10; ++t) {
;         constexpr int dummy = 0; (void)dummy;
;         const int rel = t - PAR;
;         if (rel < 0 || rel > 8) { sc[t] = (f32x4){0.f, 0.f, 0.f, 0.f}; continue; }
;         const bf16* kp = KS + (16 * (tb + t) + fr) * KS_STRIDE + 8 * fq;
;         const bf16x8 k0 = *(const bf16x8*)kp, k1 = *(const bf16x8*)(kp + 32);
;         f32x4 acc = (f32x4){0.f, 0.f, 0.f, 0.f};
;         acc = MFMA16(k0, qf[0], acc); acc = MFMA16(k1, qf[1], acc);
;         const bool tv = (n > 0) || (tb + t >= 8);
; #pragma unroll
;         for (int r = 0; r < 4; ++r) { bool valid = tv; if (rel == 0) valid = valid && (e0 + r >= 1); if (rel == 8) valid = valid && (e0 + r <= 0);
;             const float v = valid ? acc[r] + bp[16 * (8 - rel) + (3 - r)] : -1e30f; acc[r] = v; mx = fmaxf(mx, v); }
;         sc[t] = acc;
	ds_read2_b32 v[72:73], v186 offset0:51 offset1:50
	ds_read2_b32 v[74:75], v186 offset0:49 offset1:48
	ds_read2_b32 v[148:149], v186 offset0:35 offset1:34
	ds_read2_b32 v[150:151], v186 offset0:33 offset1:32
	ds_read2_b32 v[152:153], v186 offset0:19 offset1:18
	ds_read2_b32 v[154:155], v186 offset0:17 offset1:16
	ds_read2_b32 v[156:157], v186 offset0:3 offset1:2
	ds_read2_b32 v[158:159], v186 offset0:1 offset1:0
	s_waitcnt lgkmcnt(0)
	v_cndmask_b32_e64 v84, v195, v84, s[40:41]
	v_cndmask_b32_e64 v156, v156, v195, s[40:41]
	v_cndmask_b32_e64 v85, v195, v85, s[42:43]
	v_cndmask_b32_e64 v157, v157, v195, s[42:43]
	v_cndmask_b32_e64 v86, v195, v86, s[44:45]
	v_cndmask_b32_e64 v158, v158, v195, s[44:45]
	v_cndmask_b32_e64 v87, v195, v87, s[46:47]
	v_cndmask_b32_e64 v159, v159, v195, s[46:47]
	ds_read_b128 v[212:215], v185 offset:0
	ds_read_b128 v[216:219], v185 offset:64
	ds_read_b128 v[220:223], v185 offset:2304
	ds_read_b128 v[224:227], v185 offset:2368
	ds_read_b128 v[228:231], v185 offset:4608
	ds_read_b128 v[232:235], v185 offset:4672
	ds_read_b128 v[48:51], v185 offset:6912
	ds_read_b128 v[52:55], v185 offset:6976
	ds_read_b128 v[56:59], v185 offset:9216
	ds_read_b128 v[60:63], v185 offset:9280
	ds_read_b128 v[64:67], v185 offset:11520
	ds_read_b128 v[68:71], v185 offset:11584
	s_waitcnt lgkmcnt(6)
	v_mfma_f32_16x16x32_bf16 v[4:7], v[212:215], v[116:119], v[84:87]
	v_mfma_f32_16x16x32_bf16 v[8:11], v[220:223], v[116:119], v[88:91]
	v_mfma_f32_16x16x32_bf16 v[12:15], v[228:231], v[116:119], v[92:95]
	v_mfma_f32_16x16x32_bf16 v[4:7], v[216:219], v[120:123], v[4:7]
	v_mfma_f32_16x16x32_bf16 v[8:11], v[224:227], v[120:123], v[8:11]
	v_mfma_f32_16x16x32_bf16 v[12:15], v[232:235], v[120:123], v[12:15]
	ds_read_b128 v[212:215], v185 offset:13824
	ds_read_b128 v[216:219], v185 offset:13888
	ds_read_b128 v[220:223], v185 offset:16128
	ds_read_b128 v[224:227], v185 offset:16192
	ds_read_b128 v[228:231], v185 offset:18432
	ds_read_b128 v[232:235], v185 offset:18496
	s_waitcnt lgkmcnt(6)
	v_mfma_f32_16x16x32_bf16 v[16:19], v[48:51], v[116:119], v[96:99]
	v_mfma_f32_16x16x32_bf16 v[20:23], v[56:59], v[116:119], v[40:43]
	v_mfma_f32_16x16x32_bf16 v[24:27], v[64:67], v[116:119], v[72:75]
	v_mfma_f32_16x16x32_bf16 v[16:19], v[52:55], v[120:123], v[16:19]
	v_mfma_f32_16x16x32_bf16 v[20:23], v[60:63], v[120:123], v[20:23]
	v_mfma_f32_16x16x32_bf16 v[24:27], v[68:71], v[120:123], v[24:27]
	s_cmp_lg_u64 s[36:37], 0
	s_cbranch_scc1 .Lat2_nofix_0_0
	s_add_i32 s27, s26, 0
	s_cmp_ge_i32 s27, 8
	s_cbranch_scc1 .Lat2_ok_0_0
	v_mov_b32_e32 v4, v195
	v_mov_b32_e32 v5, v195
	v_mov_b32_e32 v6, v195
	v_mov_b32_e32 v7, v195
